# v8 + grid-barrier poll backoff: s_sleep 1 -> s_sleep 8 in all 25 barrier poll loops
# speedup vs baseline: 1.0110x; 1.0093x over previous
; __global__ void __launch_bounds__(512, 2) fwd_kernel(Args a) {
;     ...
;     grid.sync();
.LBB0_114:
	s_sleep 8
	global_load_dword v2, v0, s[2:3] offset:32 sc1
	s_waitcnt vmcnt(0)
	v_and_b32_e32 v2, 0xffff0000, v2
	v_cmp_ne_u32_e32 vcc, v2, v1
	s_or_b64 s[4:5], vcc, s[4:5]
	s_andn2_b64 exec, exec, s[4:5]
	s_cbranch_execnz .LBB0_114

; __device__ __forceinline__ unsigned xb_ld(unsigned* p)              { return __hip_atomic_load(p, __ATOMIC_RELAXED, __HIP_MEMORY_SCOPE_AGENT); }
; __device__ __forceinline__ void xcd_barrier_complete(unsigned* bar, unsigned x, unsigned& nloc, unsigned& nx) {
;     const unsigned G = gridDim.x * gridDim.y * gridDim.z;
;     unsigned sum, cnt, mine, sp = 0u;
;     for (;;) {
;         sum = 0u; cnt = 0u; mine = 0u;
; #pragma unroll
;         for (unsigned j = 0; j < 16; ++j) { const unsigned c = xb_ld(&bar[XB_XCNT(j)]); sum += c; cnt += (c > 0u) ? 1u : 0u; mine = (j == x) ? c : mine; }
;         if (sum == G) break;
;         __builtin_amdgcn_s_sleep(1);
;         if ((++sp & 255u) == 0u) { if (xb_ld(&bar[XB_TMO])) break; if (sp > XB_SPIN_CAP) { atomicAdd(&bar[XB_TMO], 1u); break; } }
;     }
;     nloc = mine > 0u ? mine : 1u; nx = cnt > 0u ? cnt : 1u;
; }
.LBB0_130:
	v_readlane_b32 s2, v254, 35
	v_readlane_b32 s3, v254, 36
	global_load_dword v6, v185, s[50:51] sc1
	s_waitcnt lgkmcnt(0)
	global_load_dword v0, v185, s[18:19] sc1
	global_load_dword v1, v185, s[52:53] sc1
	global_load_dword v2, v185, s[60:61] sc1
	global_load_dword v3, v185, s[62:63] sc1
	global_load_dword v4, v185, s[64:65] sc1
	global_load_dword v5, v185, s[34:35] sc1
	global_load_dword v7, v185, s[2:3] sc1
	v_readlane_b32 s2, v254, 37
	v_readlane_b32 s3, v254, 38
	s_mov_b64 s[4:5], -1
	s_waitcnt vmcnt(6)
	v_add_u32_e32 v16, v0, v6
	s_nop 1
	global_load_dword v8, v185, s[2:3] sc1
	v_readlane_b32 s2, v254, 39
	v_readlane_b32 s3, v254, 40
	s_waitcnt vmcnt(6)
	v_add_u32_e32 v16, v16, v1
	s_waitcnt vmcnt(5)
	v_add_u32_e32 v16, v16, v2
	s_waitcnt vmcnt(4)
	v_add_u32_e32 v16, v16, v3
	s_waitcnt vmcnt(3)
	v_add_u32_e32 v16, v16, v4
	s_waitcnt vmcnt(2)
	v_add_u32_e32 v16, v16, v5
	global_load_dword v9, v185, s[2:3] sc1
	v_readlane_b32 s2, v254, 41
	v_readlane_b32 s3, v254, 42
	s_waitcnt vmcnt(2)
	v_add_u32_e32 v16, v16, v7
	s_waitcnt vmcnt(1)
	v_add_u32_e32 v16, v16, v8
	s_nop 0
	global_load_dword v10, v185, s[2:3] sc1
	v_readlane_b32 s2, v254, 43
	v_readlane_b32 s3, v254, 44
	s_waitcnt vmcnt(1)
	v_add_u32_e32 v16, v16, v9
	s_nop 2
	global_load_dword v11, v185, s[2:3] sc1
	v_readlane_b32 s2, v254, 45
	v_readlane_b32 s3, v254, 46
	s_waitcnt vmcnt(1)
	v_add_u32_e32 v16, v16, v10
	s_nop 2
	global_load_dword v12, v185, s[2:3] sc1
	v_readlane_b32 s2, v254, 47
	v_readlane_b32 s3, v254, 48
	s_waitcnt vmcnt(1)
	v_add_u32_e32 v16, v16, v11
	s_nop 2
	global_load_dword v13, v185, s[2:3] sc1
	v_readlane_b32 s2, v254, 49
	v_readlane_b32 s3, v254, 50
	s_waitcnt vmcnt(1)
	v_add_u32_e32 v16, v16, v12
	s_nop 2
	global_load_dword v14, v185, s[2:3] sc1
	v_readlane_b32 s2, v254, 51
	v_readlane_b32 s3, v254, 52
	s_waitcnt vmcnt(1)
	v_add_u32_e32 v16, v16, v13
	s_nop 2
	global_load_dword v15, v185, s[2:3] sc1
	s_mov_b64 s[2:3], -1
	s_waitcnt vmcnt(1)
	v_add_u32_e32 v16, v16, v14
	s_waitcnt vmcnt(0)
	v_add_u32_e32 v16, v16, v15
	v_cmp_eq_u32_e32 vcc, s86, v16
	s_cbranch_vccnz .LBB0_129
	s_and_b32 s2, s8, 0xff
	s_cmp_eq_u32 s2, 0
	s_mov_b64 s[2:3], -1
	s_mov_b64 s[6:7], -1
	s_sleep 8
	s_cbranch_scc0 .LBB0_134
	global_load_dword v16, v185, s[92:93] sc1
	s_waitcnt vmcnt(0)
	v_cmp_eq_u32_e32 vcc, 0, v16
	s_cbranch_vccnz .LBB0_136
	s_mov_b64 s[6:7], 0

; __device__ __forceinline__ unsigned xb_ld(unsigned* p)              { return __hip_atomic_load(p, __ATOMIC_RELAXED, __HIP_MEMORY_SCOPE_AGENT); }
; __device__ __forceinline__ unsigned xb_add(unsigned* p, unsigned v) { return __hip_atomic_fetch_add(p, v, __ATOMIC_RELAXED, __HIP_MEMORY_SCOPE_AGENT); }
; #define XB_SPIN(cond, bar) do { unsigned _sp = 0; while (cond) { __builtin_amdgcn_s_sleep(1); \
;     if ((++_sp & 255u) == 0u) { if (xb_ld(&(bar)[XB_TMO])) break; if (_sp > XB_SPIN_CAP) { atomicAdd(&(bar)[XB_TMO], 1u); break; } } } } while (0)
; __device__ __forceinline__ void xcd_barrier(const XcdBarrier& b) {
;     ...
;         if (old + 1u == (gen + 1u) * nloc) {
;             __builtin_amdgcn_fence(__ATOMIC_RELEASE, "agent");
;             asm volatile("s_waitcnt vmcnt(0)" ::: "memory");
;             const unsigned og = xb_add(&bar[XB_TOP], 1u);
;             const unsigned tg = og / nx;
;             if (og + 1u == (tg + 1u) * nx) xb_add(&bar[XB_TOPGEN], 1u);
;             else XB_SPIN(xb_ld(&bar[XB_TOPGEN]) == tg, bar);
;             __builtin_amdgcn_fence(__ATOMIC_ACQUIRE, "agent");
;             xb_add(&bar[XB_XGEN(b.x)], 1u);
;             asm volatile("s_waitcnt vmcnt(0)" ::: "memory");
;         } else {
;             XB_SPIN(xb_ld(&bar[XB_XGEN(b.x)]) == gen, bar);
;             __builtin_amdgcn_fence(__ATOMIC_ACQUIRE, "agent");
;             asm volatile("s_waitcnt vmcnt(0)" ::: "memory");
;         }
.LBB0_148:
	s_and_b32 s12, s16, 0xff
	s_mov_b64 s[10:11], -1
	s_cmp_lg_u32 s12, 0
	s_mov_b64 s[14:15], -1
	s_sleep 8
	s_cbranch_scc1 .LBB0_151
	global_load_dword v0, v185, s[92:93] sc1
	s_waitcnt vmcnt(0)
	v_cmp_eq_u32_e32 vcc, 0, v0
	s_cbranch_vccnz .LBB0_153
	s_mov_b64 s[14:15], 0
	s_mov_b64 s[12:13], -1

; __device__ __forceinline__ unsigned xb_ld(unsigned* p)              { return __hip_atomic_load(p, __ATOMIC_RELAXED, __HIP_MEMORY_SCOPE_AGENT); }
; __device__ __forceinline__ void xcd_barrier_complete(unsigned* bar, unsigned x, unsigned& nloc, unsigned& nx) {
;     const unsigned G = gridDim.x * gridDim.y * gridDim.z;
;     unsigned sum, cnt, mine, sp = 0u;
;     for (;;) {
;         sum = 0u; cnt = 0u; mine = 0u;
; #pragma unroll
;         for (unsigned j = 0; j < 16; ++j) { const unsigned c = xb_ld(&bar[XB_XCNT(j)]); sum += c; cnt += (c > 0u) ? 1u : 0u; mine = (j == x) ? c : mine; }
;         if (sum == G) break;
;         __builtin_amdgcn_s_sleep(1);
;         if ((++sp & 255u) == 0u) { if (xb_ld(&bar[XB_TMO])) break; if (sp > XB_SPIN_CAP) { atomicAdd(&bar[XB_TMO], 1u); break; } }
;     }
;     nloc = mine > 0u ? mine : 1u; nx = cnt > 0u ? cnt : 1u;
; }
.LBB0_449:
	v_readlane_b32 s2, v254, 35
	v_readlane_b32 s3, v254, 36
	global_load_dword v6, v185, s[50:51] sc1
	s_waitcnt lgkmcnt(0)
	global_load_dword v0, v185, s[18:19] sc1
	global_load_dword v1, v185, s[52:53] sc1
	global_load_dword v2, v185, s[60:61] sc1
	global_load_dword v3, v185, s[62:63] sc1
	global_load_dword v4, v185, s[64:65] sc1
	global_load_dword v5, v185, s[10:11] sc1
	global_load_dword v7, v185, s[2:3] sc1
	v_readlane_b32 s2, v254, 37
	v_readlane_b32 s3, v254, 38
	s_mov_b64 s[4:5], -1
	s_waitcnt vmcnt(6)
	v_add_u32_e32 v16, v0, v6
	s_nop 1
	global_load_dword v8, v185, s[2:3] sc1
	v_readlane_b32 s2, v254, 39
	v_readlane_b32 s3, v254, 40
	s_waitcnt vmcnt(6)
	v_add_u32_e32 v16, v16, v1
	s_waitcnt vmcnt(5)
	v_add_u32_e32 v16, v16, v2
	s_waitcnt vmcnt(4)
	v_add_u32_e32 v16, v16, v3
	s_waitcnt vmcnt(3)
	v_add_u32_e32 v16, v16, v4
	s_waitcnt vmcnt(2)
	v_add_u32_e32 v16, v16, v5
	global_load_dword v9, v185, s[2:3] sc1
	v_readlane_b32 s2, v254, 41
	v_readlane_b32 s3, v254, 42
	s_waitcnt vmcnt(2)
	v_add_u32_e32 v16, v16, v7
	s_waitcnt vmcnt(1)
	v_add_u32_e32 v16, v16, v8
	s_nop 0
	global_load_dword v10, v185, s[2:3] sc1
	v_readlane_b32 s2, v254, 43
	v_readlane_b32 s3, v254, 44
	s_waitcnt vmcnt(1)
	v_add_u32_e32 v16, v16, v9
	s_nop 2
	global_load_dword v11, v185, s[2:3] sc1
	v_readlane_b32 s2, v254, 45
	v_readlane_b32 s3, v254, 46
	s_waitcnt vmcnt(1)
	v_add_u32_e32 v16, v16, v10
	s_nop 2
	global_load_dword v12, v185, s[2:3] sc1
	v_readlane_b32 s2, v254, 47
	v_readlane_b32 s3, v254, 48
	s_waitcnt vmcnt(1)
	v_add_u32_e32 v16, v16, v11
	s_nop 2
	global_load_dword v13, v185, s[2:3] sc1
	v_readlane_b32 s2, v254, 49
	v_readlane_b32 s3, v254, 50
	s_waitcnt vmcnt(1)
	v_add_u32_e32 v16, v16, v12
	s_nop 2
	global_load_dword v14, v185, s[2:3] sc1
	v_readlane_b32 s2, v254, 51
	v_readlane_b32 s3, v254, 52
	s_waitcnt vmcnt(1)
	v_add_u32_e32 v16, v16, v13
	s_nop 2
	global_load_dword v15, v185, s[2:3] sc1
	s_mov_b64 s[2:3], -1
	s_waitcnt vmcnt(1)
	v_add_u32_e32 v16, v16, v14
	s_waitcnt vmcnt(0)
	v_add_u32_e32 v16, v16, v15
	v_cmp_eq_u32_e32 vcc, s86, v16
	s_cbranch_vccnz .LBB0_448
	s_and_b32 s2, s8, 0xff
	s_cmp_eq_u32 s2, 0
	s_mov_b64 s[2:3], -1
	s_mov_b64 s[6:7], -1
	s_sleep 8
	s_cbranch_scc0 .LBB0_453
	global_load_dword v16, v185, s[92:93] sc1
	s_waitcnt vmcnt(0)
	v_cmp_eq_u32_e32 vcc, 0, v16
	s_cbranch_vccnz .LBB0_455
	s_mov_b64 s[6:7], 0
